# MFMA/LDS interleave (7.5/6.1): attention loop's K/V LDS staging writes moved from the pre-barrier tail into the middle of the P.V MFMA segment
# baseline (speedup 1.0000x reference)
; #define LAS __attribute__((address_space(3)))
; #define MFMA32(a, b, c) __builtin_amdgcn_mfma_f32_32x32x16_bf16((a), (b), (c), 0, 0, 0)
; #define ATT_VLOADH(hs, buf) do { const LAS unsigned char* vp_ = vA + ((((hs) >> 1) >> 1) * 32 + 16 * (((hs) >> 1) & 1)) * VSTR + ((hs) & 1) * 128; \
;         _Pragma("unroll") for (int t_ = 0; t_ < 2; ++t_) vah[buf][t_] = cat8(tr_read(vp_ + t_ * 64), tr_read(vp_ + 8 * VSTR + t_ * 64)); } while (0)
; __device__ __forceinline__ void attn_unit(LAS unsigned char* lds, const bf16_t* __restrict__ proj, bf16_t* __restrict__ y, int b, int h, int qb,
;                                           float lam, const float* __restrict__ subln, float post_scale, const unsigned* __restrict__ kmax2) {
;     ...
;         const LAS unsigned char* vA = lds + (j & 1) * VSLOTB + vAo;
;         bf16x8 vah[2][2];
;         QK_TILE(j - 1);
;         ATT_VLOADH(0, 0); ATT_VLOADH(1, 1);
;         __builtin_amdgcn_sched_barrier(0);
;         float ls = 0.f;
; #pragma unroll
;         for (int hs = 0; hs < 8; ++hs) {
; #pragma unroll
;             for (int t = 0; t < 2; ++t) o[2 * (hs & 1) + t] = MFMA32(vah[hs & 1][t], pb[hs >> 1], o[2 * (hs & 1) + t]);
;             if (hs + 2 < 8) ATT_VLOADH(hs + 2, hs & 1);
; #pragma unroll
;             for (int i = 2 * hs; i < 2 * hs + 2; ++i) { s0[i] = __builtin_amdgcn_exp2f(s0[i]); s1[i] = __builtin_amdgcn_exp2f(s1[i]); ls += s0[i] + s1[i]; }
;             __builtin_amdgcn_sched_barrier(0);
;         }
.LBB0_411:
	s_nop 4
	v_max_f32_e32 v0, v80, v80
	v_max_f32_e32 v2, v96, v96
	v_max_f32_e32 v0, v2, v0
	v_max3_f32 v0, v0, v97, v81
	s_and_b32 s37, s19, 1
	v_max3_f32 v0, v0, v98, v82
	s_mul_i32 s17, s37, 0x5000
	v_max3_f32 v0, v0, v99, v83
	v_max3_f32 v0, v0, v100, v84
	v_add_u32_e32 v200, s17, v205
	v_max3_f32 v0, v0, v101, v85
	ds_read_b64_tr_b16 v[6:7], v200 offset:34816
	ds_read_b64_tr_b16 v[10:11], v200 offset:34880
	ds_read_b64_tr_b16 v[172:173], v200 offset:34944
	ds_read_b64_tr_b16 v[176:177], v200 offset:35008
	ds_read_b64_tr_b16 v[8:9], v200 offset:37376
	ds_read_b64_tr_b16 v[12:13], v200 offset:37440
	ds_read_b64_tr_b16 v[174:175], v200 offset:37504
	ds_read_b64_tr_b16 v[178:179], v200 offset:37568
	v_max3_f32 v0, v0, v102, v86
	v_max3_f32 v0, v0, v103, v87
	v_max3_f32 v0, v0, v104, v88
	v_max3_f32 v0, v0, v105, v89
	v_max3_f32 v0, v0, v106, v90
	v_max3_f32 v0, v0, v107, v91
	v_max3_f32 v0, v0, v108, v92
	v_max3_f32 v0, v0, v109, v93
	v_max3_f32 v0, v0, v110, v94
	v_max3_f32 v3, v0, v111, v95
	ds_bpermute_b32 v5, v215, v3
	s_waitcnt lgkmcnt(4)
	v_mfma_f32_32x32x16_bf16 v[64:79], v[6:9], v[156:159], v[64:79]
	ds_read_b64_tr_b16 v[180:181], v200 offset:39936
	ds_read_b64_tr_b16 v[182:183], v200 offset:42496
	ds_read_b64_tr_b16 v[220:221], v200 offset:40000
	ds_read_b64_tr_b16 v[222:223], v200 offset:42560
	v_exp_f32_e32 v4, v96
	v_exp_f32_e32 v2, v80
	v_exp_f32_e32 v0, v97
	v_exp_f32_e32 v6, v81
	v_add_f32_e32 v7, v2, v4
	s_waitcnt lgkmcnt(7)
	v_mfma_f32_32x32x16_bf16 v[48:63], v[10:13], v[156:159], v[48:63]
	v_add_f32_e64 v8, v6, v0
	v_add_f32_e64 v9, v7, v1
	v_add_f32_e64 v14, v8, v8
	v_add_f32_e64 v15, v8, v9
	s_waitcnt lgkmcnt(6)
	v_mfma_f32_32x32x16_bf16 v[32:47], v[172:175], v[156:159], v[32:47]
	v_exp_f32_e32 v10, v98
	v_exp_f32_e32 v8, v82
	v_exp_f32_e32 v14, v99
	v_exp_f32_e32 v12, v83
	v_add_f32_e32 v13, v8, v10
	v_pk_add_f32 v[80:81], v[12:13], v[14:15]
	s_waitcnt lgkmcnt(5)
	v_mfma_f32_32x32x16_bf16 v[16:31], v[176:179], v[156:159], v[16:31]
	ds_read_b64_tr_b16 v[156:157], v200 offset:40064
	ds_read_b64_tr_b16 v[158:159], v200 offset:42624
	ds_read_b64_tr_b16 v[176:177], v200 offset:40128
	ds_read_b64_tr_b16 v[178:179], v200 offset:42688
	v_add_f32_e64 v98, v80, v80
	v_add_f32_e64 v99, v80, v81
	s_waitcnt lgkmcnt(6)
	v_mfma_f32_32x32x16_bf16 v[64:79], v[180:183], v[152:155], v[64:79]
	v_exp_f32_e32 v82, v100
	v_exp_f32_e32 v80, v84
	v_exp_f32_e32 v98, v101
	v_exp_f32_e32 v96, v85
	v_add_f32_e32 v97, v80, v82
	v_pk_add_f32 v[84:85], v[96:97], v[98:99]
	s_waitcnt lgkmcnt(4)
	v_mfma_f32_32x32x16_bf16 v[48:63], v[220:223], v[152:155], v[48:63]
	ds_read_b64_tr_b16 v[180:181], v200 offset:45056
	ds_read_b64_tr_b16 v[182:183], v200 offset:47616
	ds_read_b64_tr_b16 v[220:221], v200 offset:45120
	ds_read_b64_tr_b16 v[222:223], v200 offset:47680
	v_add_f32_e64 v174, v84, v84
	v_add_f32_e64 v175, v84, v85
	s_waitcnt lgkmcnt(6)
	v_mfma_f32_32x32x16_bf16 v[32:47], v[156:159], v[152:155], v[32:47]
	ds_read_b64_tr_b16 v[156:157], v200 offset:45184
	ds_read_b64_tr_b16 v[158:159], v200 offset:47744
	ds_read_b64_tr_b16 v[224:225], v200 offset:45248
	ds_read_b64_tr_b16 v[226:227], v200 offset:47808
	v_exp_f32_e32 v100, v102
	v_exp_f32_e32 v84, v86
	v_exp_f32_e32 v174, v103
	v_exp_f32_e32 v172, v87
	v_add_f32_e32 v173, v84, v100
	s_waitcnt lgkmcnt(8)
	v_mfma_f32_32x32x16_bf16 v[16:31], v[176:179], v[152:155], v[16:31]
	s_mul_i32 s17, s16, 0x5000
	v_add3_u32 v240, v186, s17, v188
	s_bitcmp1_b32 s19, 0
	s_cselect_b32 s17, 0x4400, 0
	v_add3_u32 v241, v186, s17, v187
	s_waitcnt vmcnt(0)
	ds_write_b128 v240, v[136:139] offset:34816
	ds_write_b128 v240, v[140:143] offset:45056
	ds_write_b128 v241, v[128:131]
	ds_write_b128 v241, v[132:135] offset:8704
	v_add_f32_e64 v86, v172, v174
	v_add_f32_e64 v87, v173, v175
	v_add_f32_e64 v152, v86, v86
	v_add_f32_e64 v153, v86, v87
	s_waitcnt lgkmcnt(6)
	v_mfma_f32_32x32x16_bf16 v[64:79], v[180:183], v[148:151], v[64:79]
	v_exp_f32_e32 v102, v104
	v_exp_f32_e32 v86, v88
	v_exp_f32_e32 v152, v105
	v_exp_f32_e32 v176, v89
	v_add_f32_e32 v177, v86, v102
	v_pk_add_f32 v[88:89], v[176:177], v[152:153]
	s_waitcnt lgkmcnt(4)
	v_mfma_f32_32x32x16_bf16 v[48:63], v[220:223], v[148:151], v[48:63]
	ds_read_b64_tr_b16 v[180:181], v200 offset:50176
	ds_read_b64_tr_b16 v[182:183], v200 offset:52736
	ds_read_b64_tr_b16 v[220:221], v200 offset:50240
	ds_read_b64_tr_b16 v[222:223], v200 offset:52800
	v_add_f32_e64 v154, v88, v88
	v_add_f32_e64 v155, v88, v89
	s_waitcnt lgkmcnt(6)
	v_mfma_f32_32x32x16_bf16 v[32:47], v[156:159], v[148:151], v[32:47]
	v_exp_f32_e32 v104, v106
	v_exp_f32_e32 v88, v90
	v_exp_f32_e32 v154, v107
	v_exp_f32_e32 v178, v91
	s_waitcnt lgkmcnt(4)
	v_mfma_f32_32x32x16_bf16 v[16:31], v[224:227], v[148:151], v[16:31]
	ds_read_b64_tr_b16 v[156:157], v200 offset:50304
	ds_read_b64_tr_b16 v[158:159], v200 offset:52864
	ds_read_b64_tr_b16 v[224:225], v200 offset:50368
	ds_read_b64_tr_b16 v[226:227], v200 offset:52928
	s_waitcnt lgkmcnt(6)
	v_mfma_f32_32x32x16_bf16 v[64:79], v[180:183], v[144:147], v[64:79]
	v_exp_f32_e32 v106, v108
	v_exp_f32_e32 v90, v92
	v_exp_f32_e32 v148, v109
	v_exp_f32_e32 v180, v93
	s_waitcnt lgkmcnt(4)
	v_mfma_f32_32x32x16_bf16 v[48:63], v[220:223], v[144:147], v[48:63]
	v_add_f32_e32 v179, v88, v104
	v_add_f32_e64 v92, v178, v154
	v_add_f32_e64 v93, v179, v155
	s_waitcnt lgkmcnt(2)
	v_mfma_f32_32x32x16_bf16 v[32:47], v[156:159], v[144:147], v[32:47]
	v_pk_add_f32 v[92:93], v[92:93], v[92:93] op_sel_hi:[0,1]
	v_add_f32_e32 v181, v90, v106
	v_mov_b32_e32 v149, v93
	v_pk_add_f32 v[92:93], v[180:181], v[148:149]
	v_exp_f32_e32 v108, v110
	v_exp_f32_e32 v182, v95
	s_waitcnt lgkmcnt(0)
	v_mfma_f32_32x32x16_bf16 v[16:31], v[224:227], v[144:147], v[16:31]
	v_add_f32_e64 v144, v92, v92
	v_add_f32_e64 v145, v92, v93
	v_exp_f32_e32 v92, v94
	v_exp_f32_e32 v144, v111
	v_add_f32_e32 v183, v92, v108
	v_pk_add_f32 v[94:95], v[182:183], v[144:145]
	s_nop 0
	v_add_f32_e32 v7, v94, v95
	v_max_f32_e32 v5, v5, v5
	v_max_f32_e32 v3, v3, v5
	s_mov_b32 s17, 0x40c00000
	v_add_f32_e32 v192, v192, v7
	v_cmp_lt_f32_e32 vcc, s17, v3
	s_cbranch_vccz .LBB0_413
; #define LOADK(j) do { _Pragma("unroll") for (int i_ = 0; i_ < 2; ++i_) kreg[i_] = *(const u32x4*)(kg + (size_t)((j) * 64 + 32 * i_) * DIN); } while (0)
; #define LOADV(j) do { _Pragma("unroll") for (int i_ = 0; i_ < 2; ++i_) vreg[i_] = *(const u32x4*)(vg + (size_t)((j) * 64 + 32 * i_) * DIN); } while (0)
; #define STOREK(j) do { _Pragma("unroll") for (int i_ = 0; i_ < 2; ++i_) *(LAS u32x4*)(lds + ((j) & 1) * KSLOTB + (skey + 32 * i_) * KSTR + sc * 16) = kreg[i_]; } while (0)
; #define STOREV(j) do { _Pragma("unroll") for (int i_ = 0; i_ < 2; ++i_) *(LAS u32x4*)(lds + L_VRING + ((j) & 1) * VSLOTB + (skey + 32 * i_) * VSTR + sc * 16) = vreg[i_]; } while (0)
; __device__ __forceinline__ void attn_unit(LAS unsigned char* lds, const bf16_t* __restrict__ proj, bf16_t* __restrict__ y, int b, int h, int qb,
;                                           float lam, const float* __restrict__ subln, float post_scale, const unsigned* __restrict__ kmax2) {
;     ...
;         if (__any(mx > THR)) {
;             const float dl = fmaxf(mx, 0.f);
;             m_ref += dl;
;             const float alpha = __builtin_amdgcn_exp2f(-dl);
;             l_run *= alpha;
; #pragma unroll
;             for (int i = 0; i < 16; ++i) { s0[i] *= alpha; s1[i] *= alpha; }
; #pragma unroll
;             for (int t = 0; t < 4; ++t)
; #pragma unroll
;                 for (int i = 0; i < 16; ++i) o[t][i] *= alpha;
;         }
;         pb[0] = pack_step(s0, 0); pb[1] = pack_step(s0, 1); pb[2] = pack_step(s1, 0); pb[3] = pack_step(s1, 1);
;         STOREV(j - 1);
;         if (j - 1 > 1) { STOREK(j - 2); LOADV(j - 2); if (j - 2 > 1) LOADK(j - 3); }
	v_max_f32_e32 v3, v3, v3
	v_max_f32_e32 v3, 0, v3
	v_exp_f32_e64 v94, -v3
	v_add_f32_e32 v193, v193, v3
	v_mov_b32_e32 v109, v144
	v_mov_b32_e32 v107, v148
	v_mov_b32_e32 v105, v154
	v_mov_b32_e32 v103, v152
	v_mov_b32_e32 v101, v174
	v_mov_b32_e32 v83, v98
	v_mov_b32_e32 v11, v14
	v_mov_b32_e32 v5, v0
	v_mov_b32_e32 v93, v182
	v_mov_b32_e32 v91, v180
	v_mov_b32_e32 v89, v178
	v_mov_b32_e32 v87, v176
	v_mov_b32_e32 v85, v172
	v_mov_b32_e32 v81, v96
	v_mov_b32_e32 v9, v12
	v_mov_b32_e32 v3, v6
	v_pk_mul_f32 v[108:109], v[108:109], v[94:95] op_sel_hi:[1,0]
	v_pk_mul_f32 v[106:107], v[106:107], v[94:95] op_sel_hi:[1,0]
	v_pk_mul_f32 v[104:105], v[104:105], v[94:95] op_sel_hi:[1,0]
	v_pk_mul_f32 v[102:103], v[102:103], v[94:95] op_sel_hi:[1,0]
	v_pk_mul_f32 v[100:101], v[100:101], v[94:95] op_sel_hi:[1,0]
	v_pk_mul_f32 v[82:83], v[82:83], v[94:95] op_sel_hi:[1,0]
	v_pk_mul_f32 v[10:11], v[10:11], v[94:95] op_sel_hi:[1,0]
	v_pk_mul_f32 v[4:5], v[4:5], v[94:95] op_sel_hi:[1,0]
	v_pk_mul_f32 v[92:93], v[92:93], v[94:95] op_sel_hi:[1,0]
	v_pk_mul_f32 v[90:91], v[90:91], v[94:95] op_sel_hi:[1,0]
	v_pk_mul_f32 v[88:89], v[88:89], v[94:95] op_sel_hi:[1,0]
	v_pk_mul_f32 v[86:87], v[86:87], v[94:95] op_sel_hi:[1,0]
	v_pk_mul_f32 v[84:85], v[84:85], v[94:95] op_sel_hi:[1,0]
	v_pk_mul_f32 v[80:81], v[80:81], v[94:95] op_sel_hi:[1,0]
	v_pk_mul_f32 v[8:9], v[8:9], v[94:95] op_sel_hi:[1,0]
	v_pk_mul_f32 v[2:3], v[2:3], v[94:95] op_sel_hi:[1,0]
	v_pk_mul_f32 v[78:79], v[94:95], v[78:79] op_sel_hi:[0,1]
	v_pk_mul_f32 v[76:77], v[94:95], v[76:77] op_sel_hi:[0,1]
	v_pk_mul_f32 v[74:75], v[94:95], v[74:75] op_sel_hi:[0,1]
	v_pk_mul_f32 v[72:73], v[94:95], v[72:73] op_sel_hi:[0,1]
	v_pk_mul_f32 v[70:71], v[94:95], v[70:71] op_sel_hi:[0,1]
	v_pk_mul_f32 v[68:69], v[94:95], v[68:69] op_sel_hi:[0,1]
	v_pk_mul_f32 v[66:67], v[94:95], v[66:67] op_sel_hi:[0,1]
	v_pk_mul_f32 v[64:65], v[94:95], v[64:65] op_sel_hi:[0,1]
	v_pk_mul_f32 v[62:63], v[94:95], v[62:63] op_sel_hi:[0,1]
	v_pk_mul_f32 v[60:61], v[94:95], v[60:61] op_sel_hi:[0,1]
	v_pk_mul_f32 v[58:59], v[94:95], v[58:59] op_sel_hi:[0,1]
	v_pk_mul_f32 v[56:57], v[94:95], v[56:57] op_sel_hi:[0,1]
	v_pk_mul_f32 v[54:55], v[94:95], v[54:55] op_sel_hi:[0,1]
	v_pk_mul_f32 v[52:53], v[94:95], v[52:53] op_sel_hi:[0,1]
	v_pk_mul_f32 v[50:51], v[94:95], v[50:51] op_sel_hi:[0,1]
	v_pk_mul_f32 v[48:49], v[94:95], v[48:49] op_sel_hi:[0,1]
	v_pk_mul_f32 v[46:47], v[94:95], v[46:47] op_sel_hi:[0,1]
	v_pk_mul_f32 v[44:45], v[94:95], v[44:45] op_sel_hi:[0,1]
	v_pk_mul_f32 v[42:43], v[94:95], v[42:43] op_sel_hi:[0,1]
	v_pk_mul_f32 v[40:41], v[94:95], v[40:41] op_sel_hi:[0,1]
	v_pk_mul_f32 v[38:39], v[94:95], v[38:39] op_sel_hi:[0,1]
	v_pk_mul_f32 v[36:37], v[94:95], v[36:37] op_sel_hi:[0,1]
	v_pk_mul_f32 v[34:35], v[94:95], v[34:35] op_sel_hi:[0,1]
	v_pk_mul_f32 v[32:33], v[94:95], v[32:33] op_sel_hi:[0,1]
	v_pk_mul_f32 v[30:31], v[94:95], v[30:31] op_sel_hi:[0,1]
	v_pk_mul_f32 v[28:29], v[94:95], v[28:29] op_sel_hi:[0,1]
	v_pk_mul_f32 v[26:27], v[94:95], v[26:27] op_sel_hi:[0,1]
	v_pk_mul_f32 v[24:25], v[94:95], v[24:25] op_sel_hi:[0,1]
	v_pk_mul_f32 v[22:23], v[94:95], v[22:23] op_sel_hi:[0,1]
	v_pk_mul_f32 v[20:21], v[94:95], v[20:21] op_sel_hi:[0,1]
	v_pk_mul_f32 v[18:19], v[94:95], v[18:19] op_sel_hi:[0,1]
	v_pk_mul_f32 v[16:17], v[94:95], v[16:17] op_sel_hi:[0,1]
	v_mul_f32_e32 v192, v192, v94
	v_mov_b32_e32 v6, v3
	v_mov_b32_e32 v12, v9
	v_mov_b32_e32 v96, v81
	v_mov_b32_e32 v172, v85
	v_mov_b32_e32 v176, v87
	v_mov_b32_e32 v178, v89
	v_mov_b32_e32 v180, v91
	v_mov_b32_e32 v182, v93
	v_mov_b32_e32 v0, v5
	v_mov_b32_e32 v14, v11
	v_mov_b32_e32 v98, v83
	v_mov_b32_e32 v174, v101
	v_mov_b32_e32 v152, v103
	v_mov_b32_e32 v154, v105
	v_mov_b32_e32 v148, v107
	v_mov_b32_e32 v144, v109
.LBB0_413:
	v_cvt_pk_bf16_f32 v156, v4, v0
	s_cmp_lt_i32 s19, 3
	v_cvt_pk_bf16_f32 v157, v10, v14
	v_cvt_pk_bf16_f32 v158, v82, v98
	v_cvt_pk_bf16_f32 v159, v100, v174
	v_cvt_pk_bf16_f32 v152, v102, v152
	v_cvt_pk_bf16_f32 v153, v104, v154
	v_cvt_pk_bf16_f32 v154, v106, v148
	v_cvt_pk_bf16_f32 v155, v108, v144
	v_cvt_pk_bf16_f32 v148, v2, v6
	v_cvt_pk_bf16_f32 v149, v8, v12
	v_cvt_pk_bf16_f32 v150, v80, v96
	v_cvt_pk_bf16_f32 v151, v84, v172
	v_cvt_pk_bf16_f32 v144, v86, v176
	v_cvt_pk_bf16_f32 v145, v88, v178
	v_cvt_pk_bf16_f32 v146, v90, v180
	v_cvt_pk_bf16_f32 v147, v92, v182
	s_cbranch_scc1 .LBB0_416
	s_add_i32 s16, s25, s24
	s_add_i32 s17, s16, 0xfc0
	v_mad_i64_i32 v[2:3], s[38:39], s17, v213, v[166:167]
	s_add_i32 s17, s16, 0xfe0
	global_load_dwordx4 v[136:139], v[2:3], off
	v_mad_i64_i32 v[2:3], s[38:39], s17, v213, v[166:167]
	global_load_dwordx4 v[140:143], v[2:3], off
	s_cmp_eq_u32 s26, s33
	s_cbranch_scc1 .LBB0_416
	s_add_i32 s17, s16, 0xf80
	v_mad_i64_i32 v[2:3], s[38:39], s17, v213, v[164:165]
	s_addk_i32 s16, 0xfa0
	v_mad_i64_i32 v[4:5], s[16:17], s16, v213, v[164:165]
	global_load_dwordx4 v[128:131], v[2:3], off offset:2048
	global_load_dwordx4 v[132:135], v[4:5], off offset:2048
